# baseline (speedup 1.0000x reference)
; #define otid() otid_w(p.wv)
; __device__ __forceinline__ void norm_phase(const Params& p, const float* hl, const float* hcs, int li, int which, int row0, int nrows, float* ccopy) {
;   const int tid = otid();
;   int wave = tid >> 6, lane = tid & 63;
;   const float* g = p.norm_g + (li * 3 + which) * D;
;   const int nwv = __builtin_amdgcn_readfirstlane((int)gridDim.x) * (NT / 64);
;   for (int row = row0 + blockIdx.x * (NT / 64) + wave; row < nrows; row += nwv) {
;     bool isc = row >= TL;
;     int mr = isc ? 8 : (row >> 12);
;     const float* src = isc ? hcs + (size_t)(row - TL) * D : hl + (size_t)row * D;
;     const float* md = p.mod + (size_t)(li * 9 + mr) * MODW + which * 3 * D;
;     float4 v[4];
;     float ss = 0.f;
; #pragma unroll
;     for (int i = 0; i < 4; i++) {
;       v[i] = ((const float4*)src)[lane + i * 64];
;       if (ccopy && isc) ((float4*)(ccopy + (size_t)(row - TL) * D))[lane + i * 64] = v[i];
;       ss += v[i].x * v[i].x + v[i].y * v[i].y + v[i].z * v[i].z + v[i].w * v[i].w;
;     }
; #pragma unroll
;     for (int m = 32; m >= 1; m >>= 1) ss += __shfl_xor(ss, m);
;     float rstd = rsqrtf(ss * (1.f / D) + 1e-6f);
; #pragma unroll
;     for (int i = 0; i < 4; i++) {
;       int col = (lane + i * 64) * 4;
;       float4 g4 = *(const float4*)(g + col), sh = *(const float4*)(md + col), sc = *(const float4*)(md + D + col);
;       float y0 = v[i].x * rstd * g4.x * (1.f + sc.x) + sh.x;
;       float y1 = v[i].y * rstd * g4.y * (1.f + sc.y) + sh.y;
;       float y2 = v[i].z * rstd * g4.z * (1.f + sc.z) + sh.z;
;       float y3 = v[i].w * rstd * g4.w * (1.f + sc.w) + sh.w;
;       *(uint2*)(p.z + (size_t)row * D + col) = make_uint2(pack2(y0, y1), pack2(y2, y3));
;     }
;   }
.LBB0_113:
	s_or_b64 exec, exec, s[2:3]
	s_barrier
	v_mbcnt_lo_u32_b32 v0, -1, 0
	v_mbcnt_hi_u32_b32 v0, -1, v0
	s_load_dword s0, s[0:1], 0x178
	v_readlane_b32 s2, v255, 9
	s_lshl_b32 s28, s57, 3
	s_waitcnt lgkmcnt(0)
	v_writelane_b32 v255, s0, 27
	v_add_u32_e32 v1, s2, v0
	v_ashrrev_i32_e32 v1, 6, v1
	v_add_u32_e32 v16, s28, v1
	s_mov_b32 s0, 0x8800
	v_cmp_gt_i32_e32 vcc, s0, v16
	s_and_saveexec_b64 s[2:3], vcc
	s_cbranch_execz .LBB0_128
	v_mbcnt_lo_u32_b32 v1, -1, 0
	v_mbcnt_hi_u32_b32 v1, -1, v1
	v_and_b32_e32 v2, 64, v1
	v_add_u32_e32 v3, 64, v2
	v_xor_b32_e32 v4, 32, v1
	v_cmp_lt_i32_e32 vcc, v4, v3
	v_readlane_b32 s12, v254, 6
	v_ashrrev_i32_e32 v17, 31, v16
	v_cndmask_b32_e32 v4, v1, v4, vcc
	v_lshlrev_b32_e32 v38, 2, v4
	v_xor_b32_e32 v4, 16, v1
	v_cmp_lt_i32_e32 vcc, v4, v3
	v_readlane_b32 s0, v255, 27
	v_readlane_b32 s13, v254, 7
	v_cndmask_b32_e32 v4, v1, v4, vcc
	v_lshlrev_b32_e32 v39, 2, v4
	v_xor_b32_e32 v4, 8, v1
	v_cmp_lt_i32_e32 vcc, v4, v3
	v_lshlrev_b64 v[10:11], 12, v[16:17]
	s_lshl_b32 s4, s0, 3
	v_cndmask_b32_e32 v4, v1, v4, vcc
	v_lshlrev_b32_e32 v40, 2, v4
	v_xor_b32_e32 v4, 4, v1
	v_cmp_lt_i32_e32 vcc, v4, v3
	v_and_b32_e32 v0, 63, v0
	v_lshl_add_u64 v[22:23], s[12:13], 0, v[10:11]
	v_cndmask_b32_e32 v4, v1, v4, vcc
	v_lshlrev_b32_e32 v41, 2, v4
	v_xor_b32_e32 v4, 2, v1
	v_cmp_lt_i32_e32 vcc, v4, v3
	v_lshlrev_b64 v[10:11], 11, v[16:17]
	s_cmp_lg_u64 s[78:79], 0
	v_cndmask_b32_e32 v4, v1, v4, vcc
	v_lshlrev_b32_e32 v42, 2, v4
	v_xor_b32_e32 v4, 1, v1
	v_lshlrev_b32_e32 v2, 2, v0
	v_cmp_lt_i32_e32 vcc, v4, v3
	v_lshl_or_b32 v10, v0, 3, v10
	s_cselect_b64 s[8:9], -1, 0
	v_mov_b32_e32 v19, 0
	v_lshlrev_b32_e32 v18, 4, v0
	v_readlane_b32 s14, v254, 8
	v_readlane_b32 s15, v254, 9
	v_readlane_b32 s18, v254, 12
	v_readlane_b32 s19, v254, 13
	v_readlane_b32 s20, v254, 14
	v_readlane_b32 s24, v254, 18
	v_readlane_b32 s25, v254, 19
	v_cndmask_b32_e32 v1, v1, v4, vcc
	v_or_b32_e32 v4, 0x100, v2
	v_or_b32_e32 v6, 0x200, v2
	v_or_b32_e32 v8, 0x300, v2
	s_ashr_i32 s5, s4, 31
	v_lshl_add_u64 v[10:11], s[80:81], 0, v[10:11]
	s_mov_b64 s[0:1], 0x400
	s_mov_b64 s[6:7], 0
	v_lshl_add_u64 v[20:21], s[24:25], 0, v[18:19]
	v_lshlrev_b32_e32 v43, 2, v1
	s_lshl_b64 s[10:11], s[4:5], 12
	v_lshl_add_u64 v[24:25], v[10:11], 0, s[0:1]
	s_lshl_b64 s[12:13], s[4:5], 11
	s_movk_i32 s5, 0x7fff
	s_mov_b32 s18, 0x8000
	v_lshlrev_b32_e32 v26, 4, v0
	v_mov_b32_e32 v27, v19
	v_mov_b32_e32 v17, 0x358637bd
	s_mov_b32 s19, 0x800000
	s_mov_b64 s[14:15], 0x1000
	v_lshlrev_b32_e32 v28, 2, v2
	v_mov_b32_e32 v29, v19
	v_lshlrev_b32_e32 v30, 2, v4
	v_mov_b32_e32 v31, v19
	v_lshlrev_b32_e32 v32, 2, v6
	v_mov_b32_e32 v33, v19
	v_lshlrev_b32_e32 v34, 2, v8
	v_mov_b32_e32 v35, v19
	s_mov_b32 s20, 0x87ff
	v_readlane_b32 s16, v254, 10
	v_readlane_b32 s17, v254, 11
	v_readlane_b32 s21, v254, 15
	v_readlane_b32 s22, v254, 16
	v_readlane_b32 s23, v254, 17
	v_readlane_b32 s26, v254, 20
	v_readlane_b32 s27, v254, 21
	v_lshl_add_u64 v[132:133], v[22:23], 0, v[26:27]
	global_load_dwordx4 v[116:119], v[132:133], off
	global_load_dwordx4 v[120:123], v[132:133], off offset:1024
	global_load_dwordx4 v[124:127], v[132:133], off offset:2048
	global_load_dwordx4 v[128:131], v[132:133], off offset:3072
	global_load_dword v134, v[20:21], off
	global_load_dword v134, v[20:21], off
	global_load_dword v134, v[20:21], off
	global_load_dword v134, v[20:21], off
	s_branch .LBB0_116
.LBB0_115:
	s_or_b64 exec, exec, s[16:17]
	v_min_i32_e32 v18, 0x8000, v16
	v_ashrrev_i32_e32 v18, 12, v18
	v_mul_hi_i32_i24_e32 v37, 0x9000, v18
	v_mul_i32_i24_e32 v36, 0x9000, v18
	v_lshl_add_u64 v[36:37], s[76:77], 0, v[36:37]
	v_lshl_add_u64 v[56:57], v[36:37], 0, s[14:15]
	v_lshl_add_u64 v[48:49], v[56:57], 0, v[28:29]
	global_load_dwordx4 v[44:47], v[20:21], off
	v_lshl_add_u64 v[36:37], v[36:37], 0, v[28:29]
	global_load_dwordx4 v[48:51], v[48:49], off
	s_waitcnt vmcnt(5)
	v_pk_mul_f32 v[58:59], v[12:13], v[12:13]
	global_load_dwordx4 v[52:55], v[36:37], off
	v_lshl_add_u64 v[114:115], v[56:57], 0, v[30:31]
	v_lshl_add_u64 v[110:111], v[56:57], 0, v[32:33]
	v_lshl_add_u64 v[112:113], v[56:57], 0, v[34:35]
	global_load_dwordx4 v[74:77], v[20:21], off offset:1024
	global_load_dwordx4 v[78:81], v[114:115], off
	global_load_dwordx4 v[82:85], v[36:37], off offset:1024
	global_load_dwordx4 v[86:89], v[20:21], off offset:2048
	global_load_dwordx4 v[90:93], v[110:111], off
	global_load_dwordx4 v[94:97], v[36:37], off offset:2048
	global_load_dwordx4 v[98:101], v[20:21], off offset:3072
	global_load_dwordx4 v[102:105], v[112:113], off
	global_load_dwordx4 v[106:109], v[36:37], off offset:3072
	v_readfirstlane_b32 s0, v16
	s_add_i32 s0, s0, s4
	s_cmp_lt_i32 s0, s18
	s_cbranch_scc0 .Lnorm_nopf
	v_lshl_add_u64 v[132:133], v[22:23], 0, s[10:11]
	v_lshl_add_u64 v[132:133], v[132:133], 0, v[26:27]
	global_load_dwordx4 v[116:119], v[132:133], off
	global_load_dwordx4 v[120:123], v[132:133], off offset:1024
	global_load_dwordx4 v[124:127], v[132:133], off offset:2048
	global_load_dwordx4 v[128:131], v[132:133], off offset:3072
	s_branch .Lnorm_pfdone
; #define otid() otid_w(p.wv)
; __device__ __forceinline__ void norm_phase(const Params& p, const float* hl, const float* hcs, int li, int which, int row0, int nrows, float* ccopy) {
;   const int tid = otid();
;   int wave = tid >> 6, lane = tid & 63;
;   const float* g = p.norm_g + (li * 3 + which) * D;
;   const int nwv = __builtin_amdgcn_readfirstlane((int)gridDim.x) * (NT / 64);
;   for (int row = row0 + blockIdx.x * (NT / 64) + wave; row < nrows; row += nwv) {
;     bool isc = row >= TL;
;     int mr = isc ? 8 : (row >> 12);
;     const float* src = isc ? hcs + (size_t)(row - TL) * D : hl + (size_t)row * D;
;     const float* md = p.mod + (size_t)(li * 9 + mr) * MODW + which * 3 * D;
;     float4 v[4];
;     float ss = 0.f;
; #pragma unroll
;     for (int i = 0; i < 4; i++) {
;       v[i] = ((const float4*)src)[lane + i * 64];
;       if (ccopy && isc) ((float4*)(ccopy + (size_t)(row - TL) * D))[lane + i * 64] = v[i];
;       ss += v[i].x * v[i].x + v[i].y * v[i].y + v[i].z * v[i].z + v[i].w * v[i].w;
;     }
; #pragma unroll
;     for (int m = 32; m >= 1; m >>= 1) ss += __shfl_xor(ss, m);
;     float rstd = rsqrtf(ss * (1.f / D) + 1e-6f);
; #pragma unroll
;     for (int i = 0; i < 4; i++) {
;       int col = (lane + i * 64) * 4;
;       float4 g4 = *(const float4*)(g + col), sh = *(const float4*)(md + col), sc = *(const float4*)(md + D + col);
;       float y0 = v[i].x * rstd * g4.x * (1.f + sc.x) + sh.x;
;       float y1 = v[i].y * rstd * g4.y * (1.f + sc.y) + sh.y;
;       float y2 = v[i].z * rstd * g4.z * (1.f + sc.z) + sh.z;
;       float y3 = v[i].w * rstd * g4.w * (1.f + sc.w) + sh.w;
;       *(uint2*)(p.z + (size_t)row * D + col) = make_uint2(pack2(y0, y1), pack2(y2, y3));
;     }
;   }
.Lnorm_nopf:
	global_load_dword v134, v[20:21], off
	global_load_dword v134, v[20:21], off
	global_load_dword v134, v[20:21], off
	global_load_dword v134, v[20:21], off
.Lnorm_pfdone:
	s_waitcnt vmcnt(18)
	v_pk_mul_f32 v[62:63], v[8:9], v[8:9]
	v_pk_mul_f32 v[60:61], v[14:15], v[14:15]
	v_pk_mul_f32 v[64:65], v[10:11], v[10:11]
	s_waitcnt vmcnt(17)
	v_pk_mul_f32 v[66:67], v[4:5], v[4:5]
	v_add_f32_e32 v18, v62, v63
	v_add_f32_e32 v58, v58, v59
	v_pk_mul_f32 v[68:69], v[6:7], v[6:7]
	s_waitcnt vmcnt(16)
	v_pk_mul_f32 v[70:71], v[0:1], v[0:1]
	v_add_f32_e32 v59, v66, v67
	v_add_f32_e32 v18, v18, v64
	v_add_f32_e32 v58, v58, v60
	v_pk_mul_f32 v[72:73], v[2:3], v[2:3]
	v_add_f32_e32 v62, v70, v71
	v_add_f32_e32 v59, v59, v68
	v_add_f32_e32 v18, v18, v65
	v_add_f32_e32 v58, v58, v61
	v_add_f32_e32 v60, v62, v72
	v_add_f32_e32 v59, v59, v69
	v_add_f32_e32 v18, v58, v18
	v_add_f32_e32 v60, v60, v73
	v_add_f32_e32 v18, v18, v59
	v_add_f32_e32 v18, v18, v60
	ds_bpermute_b32 v58, v38, v18
	v_add_u32_e32 v16, s4, v16
	v_lshl_add_u64 v[22:23], v[22:23], 0, s[10:11]
	s_waitcnt lgkmcnt(0)
	v_add_f32_e32 v18, v18, v58
	ds_bpermute_b32 v58, v39, v18
	s_waitcnt lgkmcnt(0)
	v_add_f32_e32 v18, v18, v58
	ds_bpermute_b32 v58, v40, v18
	s_waitcnt lgkmcnt(0)
	v_add_f32_e32 v18, v18, v58
	ds_bpermute_b32 v58, v41, v18
	s_waitcnt lgkmcnt(0)
	v_add_f32_e32 v18, v18, v58
	ds_bpermute_b32 v58, v42, v18
	s_waitcnt lgkmcnt(0)
	v_add_f32_e32 v18, v18, v58
	ds_bpermute_b32 v58, v43, v18
	s_waitcnt lgkmcnt(0)
	v_add_f32_e32 v18, v18, v58
	v_fmamk_f32 v18, v18, 0x3a800000, v17
	v_mul_f32_e32 v58, 0x4b800000, v18
	v_cmp_gt_f32_e32 vcc, s19, v18
	s_nop 1
	v_cndmask_b32_e32 v18, v18, v58, vcc
	v_rsq_f32_e32 v18, v18
	v_lshl_add_u64 v[58:59], v[56:57], 0, v[30:31]
	v_mul_f32_e32 v60, 0x45800000, v18
	v_cndmask_b32_e32 v18, v18, v60, vcc
	v_pk_mul_f32 v[12:13], v[12:13], v[18:19] op_sel_hi:[1,0]
	v_pk_mul_f32 v[14:15], v[14:15], v[18:19] op_sel_hi:[1,0]
	v_pk_mul_f32 v[8:9], v[8:9], v[18:19] op_sel_hi:[1,0]
	v_pk_mul_f32 v[10:11], v[10:11], v[18:19] op_sel_hi:[1,0]
	v_pk_mul_f32 v[4:5], v[4:5], v[18:19] op_sel_hi:[1,0]
	s_waitcnt vmcnt(4)
	v_pk_mul_f32 v[12:13], v[44:45], v[12:13]
	v_pk_mul_f32 v[14:15], v[46:47], v[14:15]
	v_pk_add_f32 v[44:45], v[48:49], 1.0 op_sel_hi:[1,0]
	v_pk_add_f32 v[46:47], v[50:51], 1.0 op_sel_hi:[1,0]
	v_pk_fma_f32 v[12:13], v[44:45], v[12:13], v[52:53]
	v_pk_fma_f32 v[14:15], v[14:15], v[46:47], v[54:55]
	v_cvt_pk_bf16_f32 v12, v12, v13
	v_cvt_pk_bf16_f32 v13, v14, v15
	global_store_dwordx2 v[24:25], v[12:13], off offset:-1024
	s_nop 0
	v_lshl_add_u64 v[52:53], v[56:57], 0, v[32:33]
	v_pk_mul_f32 v[6:7], v[6:7], v[18:19] op_sel_hi:[1,0]
	v_pk_mul_f32 v[0:1], v[0:1], v[18:19] op_sel_hi:[1,0]
	v_pk_mul_f32 v[2:3], v[2:3], v[18:19] op_sel_hi:[1,0]
	v_cmp_lt_i32_e32 vcc, s20, v16
	s_or_b64 s[6:7], vcc, s[6:7]
	v_pk_mul_f32 v[8:9], v[8:9], v[74:75]
	v_pk_add_f32 v[12:13], v[78:79], 1.0 op_sel_hi:[1,0]
	v_pk_mul_f32 v[10:11], v[10:11], v[76:77]
	v_pk_add_f32 v[14:15], v[80:81], 1.0 op_sel_hi:[1,0]
	v_pk_fma_f32 v[8:9], v[8:9], v[12:13], v[82:83]
	v_pk_fma_f32 v[10:11], v[10:11], v[14:15], v[84:85]
	v_cvt_pk_bf16_f32 v8, v8, v9
	v_cvt_pk_bf16_f32 v9, v10, v11
	global_store_dwordx2 v[24:25], v[8:9], off offset:-512
	s_nop 0
	v_lshl_add_u64 v[48:49], v[56:57], 0, v[34:35]
	v_pk_mul_f32 v[4:5], v[4:5], v[86:87]
	v_pk_add_f32 v[8:9], v[90:91], 1.0 op_sel_hi:[1,0]
	v_pk_mul_f32 v[6:7], v[6:7], v[88:89]
	v_pk_add_f32 v[10:11], v[92:93], 1.0 op_sel_hi:[1,0]
	v_pk_fma_f32 v[4:5], v[4:5], v[8:9], v[94:95]
	v_pk_fma_f32 v[6:7], v[6:7], v[10:11], v[96:97]
	v_cvt_pk_bf16_f32 v4, v4, v5
	v_cvt_pk_bf16_f32 v5, v6, v7
	global_store_dwordx2 v[24:25], v[4:5], off
	s_nop 0
	v_pk_mul_f32 v[0:1], v[0:1], v[98:99]
	v_pk_add_f32 v[4:5], v[102:103], 1.0 op_sel_hi:[1,0]
	v_pk_mul_f32 v[2:3], v[2:3], v[100:101]
	v_pk_add_f32 v[6:7], v[104:105], 1.0 op_sel_hi:[1,0]
	v_pk_fma_f32 v[0:1], v[0:1], v[4:5], v[106:107]
	v_pk_fma_f32 v[2:3], v[2:3], v[6:7], v[108:109]
	v_cvt_pk_bf16_f32 v0, v0, v1
	v_cvt_pk_bf16_f32 v1, v2, v3
	global_store_dwordx2 v[24:25], v[0:1], off offset:512
	v_lshl_add_u64 v[24:25], v[24:25], 0, s[12:13]
	s_andn2_b64 exec, exec, s[6:7]
	s_cbranch_execz .LBB0_128
.LBB0_116:
	v_readfirstlane_b32 s0, v16
	s_cmp_lt_i32 s0, s18
	s_cbranch_scc0 .Lnorm_slow
	s_waitcnt vmcnt(4)
	v_mov_b32_e32 v12, v116
	v_mov_b32_e32 v13, v117
	v_mov_b32_e32 v14, v118
	v_mov_b32_e32 v15, v119
	v_mov_b32_e32 v8, v120
	v_mov_b32_e32 v9, v121
	v_mov_b32_e32 v10, v122
	v_mov_b32_e32 v11, v123
	v_mov_b32_e32 v4, v124
	v_mov_b32_e32 v5, v125
	v_mov_b32_e32 v6, v126
	v_mov_b32_e32 v7, v127
	v_mov_b32_e32 v0, v128
	v_mov_b32_e32 v1, v129
	v_mov_b32_e32 v2, v130
	v_mov_b32_e32 v3, v131
	s_mov_b64 s[16:17], exec
	s_branch .LBB0_115
